# residual GEMM epilogues: accumulator lane permutation (128 ds_bpermute) moved after each path's first global loads are issued (gate / residual-row latency overlaps it)
# speedup vs baseline: 1.0143x; 1.0047x over previous
.LBB0_304:
	v_mbcnt_lo_u32_b32 v223, -1, 0
	v_mbcnt_hi_u32_b32 v223, -1, v223
	v_and_b32_e32 v224, 3, v223
	v_lshrrev_b32_e32 v223, 2, v223
	v_lshl_or_b32 v222, v224, 4, v223
	v_lshlrev_b32_e32 v222, 2, v222
	v_and_b32_e32 v225, 0x60, v208
	v_lshl_or_b32 v225, v224, 2, v225
	s_lshl_b32 s25, s76, 8
	s_add_i32 s38, s25, s62
	v_or_b32_e32 v192, s38, v223
	v_lshl_or_b32 v194, s77, 8, v225
	s_waitcnt lgkmcnt(0)
	s_mov_b64 s[36:37], -1
	s_andn2_b64 vcc, exec, s[34:35]
	v_ashrrev_i32_e32 v195, 31, v194
	v_or_b32_e32 v190, 16, v192
	v_or_b32_e32 v188, 32, v192
	v_or_b32_e32 v186, 48, v192
	s_cbranch_vccz .LBB0_307
	s_andn2_b64 vcc, exec, s[36:37]
	s_cbranch_vccz .LBB0_308

.LBB0_307:
	v_add_u32_e32 v214, 0xffffc000, v192
	s_ashr_i32 s31, s38, 13
	v_lshrrev_b32_e32 v134, 3, v214
	v_lshlrev_b64 v[196:197], 2, v[194:195]
	v_cmp_gt_i32_e32 vcc, s85, v192
	v_or_b32_e32 v134, 2, v134
	v_mov_b32_e32 v136, s31
	v_lshl_add_u64 v[198:199], s[18:19], 0, v[196:197]
	v_cndmask_b32_e32 v134, v134, v136, vcc
	v_mad_i64_i32 v[134:135], s[34:35], v134, s88, v[198:199]
	v_add_u32_e32 v204, 0xffffc010, v192
	global_load_dwordx4 v[210:213], v[134:135], off
	global_load_dwordx4 v[220:223], v[134:135], off offset:64
	global_load_dwordx4 v[224:227], v[134:135], off offset:512
	global_load_dwordx4 v[244:247], v[134:135], off offset:576
	v_lshrrev_b32_e32 v134, 3, v204
	v_cmp_gt_i32_e32 vcc, s85, v190
	v_add_u32_e32 v134, 2, v134
	v_add_u32_e32 v202, 0xffffc020, v192
	v_cndmask_b32_e32 v134, v134, v136, vcc
	v_mad_i64_i32 v[134:135], s[34:35], v134, s88, v[198:199]
	global_load_dwordx4 v[178:181], v[134:135], off
	global_load_dwordx4 v[174:177], v[134:135], off offset:64
	global_load_dwordx4 v[170:173], v[134:135], off offset:512
	global_load_dwordx4 v[162:165], v[134:135], off offset:576
	v_lshrrev_b32_e32 v134, 3, v202
	v_cmp_gt_i32_e32 vcc, s85, v188
	v_or_b32_e32 v134, 2, v134
	v_add_u32_e32 v200, 0xffffc030, v192
	v_cndmask_b32_e32 v134, v134, v136, vcc
	v_mad_i64_i32 v[134:135], s[34:35], v134, s88, v[198:199]
	global_load_dwordx4 v[166:169], v[134:135], off
	global_load_dwordx4 v[158:161], v[134:135], off offset:64
	global_load_dwordx4 v[154:157], v[134:135], off offset:512
	global_load_dwordx4 v[146:149], v[134:135], off offset:576
	v_lshrrev_b32_e32 v134, 3, v200
	v_cmp_gt_i32_e32 vcc, s85, v186
	v_add_u32_e32 v134, 2, v134
	s_ashr_i32 s31, s30, 31
	v_cndmask_b32_e32 v134, v134, v136, vcc
	v_mad_i64_i32 v[134:135], s[34:35], v134, s88, v[198:199]
	global_load_dwordx4 v[150:153], v[134:135], off
	global_load_dwordx4 v[142:145], v[134:135], off offset:64
	global_load_dwordx4 v[138:141], v[134:135], off offset:512
	s_nop 0
	global_load_dwordx4 v[134:137], v[134:135], off offset:576
	s_abs_i32 s30, s30
	s_mul_hi_u32 s34, s30, s72
	s_mul_i32 s35, s34, s42
	s_sub_i32 s30, s30, s35
	s_add_i32 s35, s34, 1
	s_sub_i32 s36, s30, s42
	s_cmp_ge_u32 s30, s42
	s_cselect_b32 s34, s35, s34
	s_cselect_b32 s30, s36, s30
	s_add_i32 s35, s34, 1
	s_cmp_ge_u32 s30, s42
	s_cselect_b32 s30, s35, s34
	s_xor_b32 s30, s30, s31
	s_sub_i32 s30, s30, s31
	s_ashr_i32 s31, s30, 31
	s_lshl_b64 s[30:31], s[30:31], 22
	s_add_u32 s30, s60, s30
	v_ashrrev_i32_e32 v205, 31, v204
	s_addc_u32 s31, s61, s31
	v_lshlrev_b64 v[204:205], 12, v[204:205]
	v_ashrrev_i32_e32 v215, 31, v214
	v_lshl_add_u64 v[204:205], s[30:31], 0, v[204:205]
	v_lshlrev_b64 v[214:215], 12, v[214:215]
	v_lshl_add_u64 v[204:205], v[204:205], 0, v[196:197]
	v_ashrrev_i32_e32 v203, 31, v202
	v_lshl_add_u64 v[214:215], s[30:31], 0, v[214:215]
	v_lshl_add_u64 v[214:215], v[214:215], 0, v[196:197]
	v_ashrrev_i32_e32 v201, 31, v200
	s_addk_i32 s38, 0x80
	s_ashr_i32 s34, s38, 13
	s_movk_i32 s35, 0x3f80
	v_cmp_gt_i32_e32 vcc, s35, v192
	v_mov_b32_e32 v187, s34
	v_add_u32_e32 v216, 0xffffc090, v192
	v_ashrrev_i32_e32 v217, 31, v216
	v_mbcnt_lo_u32_b32 v218, -1, 0
	v_mbcnt_hi_u32_b32 v218, -1, v218
	v_and_b32_e32 v219, 3, v218
	v_lshrrev_b32_e32 v218, 2, v218
	v_lshl_or_b32 v218, v219, 4, v218
	v_lshlrev_b32_e32 v218, 2, v218
	ds_bpermute_b32 v6, v218, v6
	ds_bpermute_b32 v7, v218, v7
	ds_bpermute_b32 v8, v218, v8
	ds_bpermute_b32 v9, v218, v9
	ds_bpermute_b32 v10, v218, v10
	ds_bpermute_b32 v11, v218, v11
	ds_bpermute_b32 v12, v218, v12
	ds_bpermute_b32 v13, v218, v13
	ds_bpermute_b32 v14, v218, v14
	ds_bpermute_b32 v15, v218, v15
	ds_bpermute_b32 v16, v218, v16
	ds_bpermute_b32 v17, v218, v17
	ds_bpermute_b32 v18, v218, v18
	ds_bpermute_b32 v19, v218, v19
	ds_bpermute_b32 v20, v218, v20
	ds_bpermute_b32 v21, v218, v21
	s_waitcnt lgkmcnt(8)
	ds_bpermute_b32 v22, v218, v22
	ds_bpermute_b32 v23, v218, v23
	ds_bpermute_b32 v24, v218, v24
	ds_bpermute_b32 v25, v218, v25
	ds_bpermute_b32 v26, v218, v26
	ds_bpermute_b32 v27, v218, v27
	ds_bpermute_b32 v28, v218, v28
	ds_bpermute_b32 v29, v218, v29
	s_waitcnt lgkmcnt(8)
	ds_bpermute_b32 v30, v218, v30
	ds_bpermute_b32 v31, v218, v31
	ds_bpermute_b32 v32, v218, v32
	ds_bpermute_b32 v33, v218, v33
	ds_bpermute_b32 v34, v218, v34
	ds_bpermute_b32 v35, v218, v35
	ds_bpermute_b32 v36, v218, v36
	ds_bpermute_b32 v37, v218, v37
	s_waitcnt lgkmcnt(8)
	ds_bpermute_b32 v38, v218, v38
	ds_bpermute_b32 v39, v218, v39
	ds_bpermute_b32 v40, v218, v40
	ds_bpermute_b32 v41, v218, v41
	ds_bpermute_b32 v42, v218, v42
	ds_bpermute_b32 v43, v218, v43
	ds_bpermute_b32 v44, v218, v44
	ds_bpermute_b32 v45, v218, v45
	s_waitcnt lgkmcnt(8)
	ds_bpermute_b32 v46, v218, v46
	ds_bpermute_b32 v47, v218, v47
	ds_bpermute_b32 v48, v218, v48
	ds_bpermute_b32 v49, v218, v49
	ds_bpermute_b32 v50, v218, v50
	ds_bpermute_b32 v51, v218, v51
	ds_bpermute_b32 v52, v218, v52
	ds_bpermute_b32 v53, v218, v53
	s_waitcnt lgkmcnt(8)
	ds_bpermute_b32 v54, v218, v54
	ds_bpermute_b32 v55, v218, v55
	ds_bpermute_b32 v56, v218, v56
	ds_bpermute_b32 v57, v218, v57
	ds_bpermute_b32 v58, v218, v58
	ds_bpermute_b32 v59, v218, v59
	ds_bpermute_b32 v60, v218, v60
	ds_bpermute_b32 v61, v218, v61
	s_waitcnt lgkmcnt(8)
	ds_bpermute_b32 v62, v218, v62
	ds_bpermute_b32 v63, v218, v63
	ds_bpermute_b32 v64, v218, v64
	ds_bpermute_b32 v65, v218, v65
	ds_bpermute_b32 v66, v218, v66
	ds_bpermute_b32 v67, v218, v67
	ds_bpermute_b32 v68, v218, v68
	ds_bpermute_b32 v69, v218, v69
	s_waitcnt lgkmcnt(8)
	ds_bpermute_b32 v70, v218, v70
	ds_bpermute_b32 v71, v218, v71
	ds_bpermute_b32 v72, v218, v72
	ds_bpermute_b32 v73, v218, v73
	ds_bpermute_b32 v74, v218, v74
	ds_bpermute_b32 v75, v218, v75
	ds_bpermute_b32 v76, v218, v76
	ds_bpermute_b32 v77, v218, v77
	s_waitcnt lgkmcnt(8)
	ds_bpermute_b32 v78, v218, v78
	ds_bpermute_b32 v79, v218, v79
	ds_bpermute_b32 v80, v218, v80
	ds_bpermute_b32 v81, v218, v81
	ds_bpermute_b32 v82, v218, v82
	ds_bpermute_b32 v83, v218, v83
	ds_bpermute_b32 v84, v218, v84
	ds_bpermute_b32 v85, v218, v85
	s_waitcnt lgkmcnt(8)
	ds_bpermute_b32 v86, v218, v86
	ds_bpermute_b32 v87, v218, v87
	ds_bpermute_b32 v88, v218, v88
	ds_bpermute_b32 v89, v218, v89
	ds_bpermute_b32 v90, v218, v90
	ds_bpermute_b32 v91, v218, v91
	ds_bpermute_b32 v92, v218, v92
	ds_bpermute_b32 v93, v218, v93
	s_waitcnt lgkmcnt(8)
	ds_bpermute_b32 v94, v218, v94
	ds_bpermute_b32 v95, v218, v95
	ds_bpermute_b32 v96, v218, v96
	ds_bpermute_b32 v97, v218, v97
	ds_bpermute_b32 v98, v218, v98
	ds_bpermute_b32 v99, v218, v99
	ds_bpermute_b32 v100, v218, v100
	ds_bpermute_b32 v101, v218, v101
	s_waitcnt lgkmcnt(8)
	ds_bpermute_b32 v102, v218, v102
	ds_bpermute_b32 v103, v218, v103
	ds_bpermute_b32 v104, v218, v104
	ds_bpermute_b32 v105, v218, v105
	ds_bpermute_b32 v106, v218, v106
	ds_bpermute_b32 v107, v218, v107
	ds_bpermute_b32 v108, v218, v108
	ds_bpermute_b32 v109, v218, v109
	s_waitcnt lgkmcnt(8)
	ds_bpermute_b32 v110, v218, v110
	ds_bpermute_b32 v111, v218, v111
	ds_bpermute_b32 v112, v218, v112
	ds_bpermute_b32 v113, v218, v113
	ds_bpermute_b32 v114, v218, v114
	ds_bpermute_b32 v115, v218, v115
	ds_bpermute_b32 v116, v218, v116
	ds_bpermute_b32 v117, v218, v117
	s_waitcnt lgkmcnt(8)
	ds_bpermute_b32 v118, v218, v118
	ds_bpermute_b32 v119, v218, v119
	ds_bpermute_b32 v120, v218, v120
	ds_bpermute_b32 v121, v218, v121
	ds_bpermute_b32 v122, v218, v122
	ds_bpermute_b32 v123, v218, v123
	ds_bpermute_b32 v124, v218, v124
	ds_bpermute_b32 v125, v218, v125
	s_waitcnt lgkmcnt(8)
	ds_bpermute_b32 v126, v218, v126
	ds_bpermute_b32 v127, v218, v127
	ds_bpermute_b32 v128, v218, v128
	ds_bpermute_b32 v129, v218, v129
	ds_bpermute_b32 v130, v218, v130
	ds_bpermute_b32 v131, v218, v131
	ds_bpermute_b32 v132, v218, v132
	ds_bpermute_b32 v133, v218, v133
	s_waitcnt lgkmcnt(0)
	s_waitcnt vmcnt(0)
	v_pk_mul_f32 v[212:213], v[132:133], v[212:213]
	v_pk_mul_f32 v[210:211], v[130:131], v[210:211]
	global_store_dwordx4 v[214:215], v[210:213], off sc1
	v_pk_mul_f32 v[180:181], v[116:117], v[180:181]
	s_nop 0
	v_pk_mul_f32 v[212:213], v[128:129], v[222:223]
	v_pk_mul_f32 v[172:173], v[108:109], v[172:173]
	v_pk_mul_f32 v[164:165], v[104:105], v[164:165]
	v_pk_mul_f32 v[162:163], v[102:103], v[162:163]
	global_store_dwordx4 v[204:205], v[162:165], off offset:576 sc1
	v_pk_mul_f32 v[170:171], v[106:107], v[170:171]
	v_pk_mul_f32 v[210:211], v[126:127], v[220:221]
	v_lshlrev_b64 v[162:163], 12, v[202:203]
	v_lshl_add_u64 v[162:163], s[30:31], 0, v[162:163]
	global_store_dwordx4 v[204:205], v[170:173], off offset:512 sc1
	v_pk_mul_f32 v[148:149], v[88:89], v[148:149]
	v_pk_mul_f32 v[146:147], v[86:87], v[146:147]
	v_lshl_add_u64 v[170:171], v[162:163], 0, v[196:197]
	global_store_dwordx4 v[214:215], v[210:213], off offset:64 sc1
	global_store_dwordx4 v[170:171], v[146:149], off offset:576 sc1
	v_pk_mul_f32 v[156:157], v[92:93], v[156:157]
	v_pk_mul_f32 v[212:213], v[124:125], v[226:227]
	v_pk_mul_f32 v[210:211], v[122:123], v[224:225]
	v_lshlrev_b64 v[146:147], 12, v[200:201]
	global_store_dwordx4 v[214:215], v[210:213], off offset:512 sc1
	v_pk_mul_f32 v[154:155], v[90:91], v[154:155]
	v_lshl_add_u64 v[146:147], s[30:31], 0, v[146:147]
	v_pk_mul_f32 v[212:213], v[120:121], v[246:247]
	v_pk_mul_f32 v[210:211], v[118:119], v[244:245]
	global_store_dwordx4 v[214:215], v[210:213], off offset:576 sc1
	global_store_dwordx4 v[170:171], v[154:157], off offset:512 sc1
	v_pk_mul_f32 v[136:137], v[72:73], v[136:137]
	v_pk_mul_f32 v[134:135], v[70:71], v[134:135]
	v_lshl_add_u64 v[154:155], v[146:147], 0, v[196:197]
	v_add_u32_e32 v214, 0xffffc080, v192
	global_store_dwordx4 v[154:155], v[134:137], off offset:576 sc1
	v_pk_mul_f32 v[178:179], v[114:115], v[178:179]
	v_pk_mul_f32 v[176:177], v[112:113], v[176:177]
	v_lshrrev_b32_e32 v134, 3, v214
	v_pk_mul_f32 v[174:175], v[110:111], v[174:175]
	v_pk_mul_f32 v[164:165], v[100:101], v[168:169]
	v_pk_mul_f32 v[162:163], v[98:99], v[166:167]
	v_pk_mul_f32 v[160:161], v[96:97], v[160:161]
	v_pk_mul_f32 v[158:159], v[94:95], v[158:159]
	v_pk_mul_f32 v[148:149], v[84:85], v[152:153]
	v_pk_mul_f32 v[146:147], v[82:83], v[150:151]
	v_pk_mul_f32 v[144:145], v[80:81], v[144:145]
	v_pk_mul_f32 v[142:143], v[78:79], v[142:143]
	v_pk_mul_f32 v[140:141], v[76:77], v[140:141]
	v_pk_mul_f32 v[138:139], v[74:75], v[138:139]
	v_or_b32_e32 v134, 2, v134
	global_store_dwordx4 v[204:205], v[178:181], off sc1
	global_store_dwordx4 v[204:205], v[174:177], off offset:64 sc1
	global_store_dwordx4 v[170:171], v[162:165], off sc1
	global_store_dwordx4 v[170:171], v[158:161], off offset:64 sc1
	global_store_dwordx4 v[154:155], v[146:149], off sc1
	global_store_dwordx4 v[154:155], v[142:145], off offset:64 sc1
	global_store_dwordx4 v[154:155], v[138:141], off offset:512 sc1
	v_cndmask_b32_e32 v134, v134, v187, vcc
	v_mad_i64_i32 v[146:147], s[34:35], v134, s88, v[198:199]
	global_load_dwordx4 v[134:137], v[146:147], off
	global_load_dwordx4 v[138:141], v[146:147], off offset:64
	global_load_dwordx4 v[142:145], v[146:147], off offset:512
	s_nop 0
	global_load_dwordx4 v[146:149], v[146:147], off offset:576
	s_movk_i32 s34, 0x3f70
	v_lshrrev_b32_e32 v150, 3, v216
	v_cmp_gt_i32_e32 vcc, s34, v192
	v_add_u32_e32 v150, 2, v150
	v_add_u32_e32 v224, 0xffffc0a0, v192
	v_cndmask_b32_e32 v150, v150, v187, vcc
	v_mad_i64_i32 v[162:163], s[34:35], v150, s88, v[198:199]
	global_load_dwordx4 v[150:153], v[162:163], off
	global_load_dwordx4 v[154:157], v[162:163], off offset:64
	global_load_dwordx4 v[158:161], v[162:163], off offset:512
	s_nop 0
	global_load_dwordx4 v[162:165], v[162:163], off offset:576
	s_movk_i32 s34, 0x3f60
	v_lshrrev_b32_e32 v166, 3, v224
	v_cmp_gt_i32_e32 vcc, s34, v192
	v_or_b32_e32 v166, 2, v166
	v_add_u32_e32 v226, 0xffffc0b0, v192
	v_cndmask_b32_e32 v166, v166, v187, vcc
	v_mad_i64_i32 v[178:179], s[34:35], v166, s88, v[198:199]
	global_load_dwordx4 v[166:169], v[178:179], off
	global_load_dwordx4 v[170:173], v[178:179], off offset:64
	global_load_dwordx4 v[174:177], v[178:179], off offset:512
	s_nop 0
	global_load_dwordx4 v[178:181], v[178:179], off offset:576
	v_lshrrev_b32_e32 v189, 3, v226
	v_cmp_gt_i32_e32 vcc, s94, v192
	v_add_u32_e32 v189, 2, v189
	v_ashrrev_i32_e32 v215, 31, v214
	v_cndmask_b32_e32 v187, v189, v187, vcc
	v_mad_i64_i32 v[220:221], s[34:35], v187, s88, v[198:199]
	global_load_dwordx4 v[198:201], v[220:221], off
	global_load_dwordx4 v[202:205], v[220:221], off offset:64
	global_load_dwordx4 v[210:213], v[220:221], off offset:512
	s_nop 0
	global_load_dwordx4 v[220:223], v[220:221], off offset:576
	v_lshlrev_b64 v[214:215], 12, v[214:215]
	v_lshl_add_u64 v[214:215], s[30:31], 0, v[214:215]
	v_lshl_add_u64 v[214:215], v[214:215], 0, v[196:197]
	v_ashrrev_i32_e32 v225, 31, v224
	v_ashrrev_i32_e32 v227, 31, v226
	s_waitcnt vmcnt(0)
	v_pk_mul_f32 v[136:137], v[68:69], v[136:137]
	v_pk_mul_f32 v[134:135], v[66:67], v[134:135]
	global_store_dwordx4 v[214:215], v[134:137], off sc1
	s_nop 1
	v_pk_mul_f32 v[136:137], v[64:65], v[140:141]
	v_pk_mul_f32 v[134:135], v[62:63], v[138:139]
	global_store_dwordx4 v[214:215], v[134:137], off offset:64 sc1
	s_nop 1
	v_pk_mul_f32 v[136:137], v[60:61], v[144:145]
	v_pk_mul_f32 v[134:135], v[58:59], v[142:143]
	global_store_dwordx4 v[214:215], v[134:137], off offset:512 sc1
	s_nop 1
	v_pk_mul_f32 v[136:137], v[56:57], v[148:149]
	v_pk_mul_f32 v[134:135], v[54:55], v[146:147]
	global_store_dwordx4 v[214:215], v[134:137], off offset:576 sc1
	s_nop 1
	v_lshlrev_b64 v[134:135], 12, v[216:217]
	v_lshl_add_u64 v[134:135], s[30:31], 0, v[134:135]
	v_lshl_add_u64 v[138:139], v[134:135], 0, v[196:197]
	v_pk_mul_f32 v[136:137], v[52:53], v[152:153]
	v_pk_mul_f32 v[134:135], v[50:51], v[150:151]
	global_store_dwordx4 v[138:139], v[134:137], off sc1
	s_nop 1
	v_pk_mul_f32 v[136:137], v[48:49], v[156:157]
	v_pk_mul_f32 v[134:135], v[46:47], v[154:155]
	global_store_dwordx4 v[138:139], v[134:137], off offset:64 sc1
	s_nop 1
	v_pk_mul_f32 v[136:137], v[44:45], v[160:161]
	v_pk_mul_f32 v[134:135], v[42:43], v[158:159]
	global_store_dwordx4 v[138:139], v[134:137], off offset:512 sc1
	s_nop 1
	v_pk_mul_f32 v[136:137], v[40:41], v[164:165]
	v_pk_mul_f32 v[134:135], v[38:39], v[162:163]
	global_store_dwordx4 v[138:139], v[134:137], off offset:576 sc1
	s_nop 1
	v_lshlrev_b64 v[134:135], 12, v[224:225]
	v_lshl_add_u64 v[134:135], s[30:31], 0, v[134:135]
	v_lshl_add_u64 v[138:139], v[134:135], 0, v[196:197]
	v_pk_mul_f32 v[136:137], v[36:37], v[168:169]
	v_pk_mul_f32 v[134:135], v[34:35], v[166:167]
	global_store_dwordx4 v[138:139], v[134:137], off sc1
	s_nop 1
	v_pk_mul_f32 v[136:137], v[32:33], v[172:173]
	v_pk_mul_f32 v[134:135], v[30:31], v[170:171]
	global_store_dwordx4 v[138:139], v[134:137], off offset:64 sc1
	s_nop 1
	v_pk_mul_f32 v[136:137], v[28:29], v[176:177]
	v_pk_mul_f32 v[134:135], v[26:27], v[174:175]
	global_store_dwordx4 v[138:139], v[134:137], off offset:512 sc1
	s_nop 1
	v_pk_mul_f32 v[136:137], v[24:25], v[180:181]
	v_pk_mul_f32 v[134:135], v[22:23], v[178:179]
	global_store_dwordx4 v[138:139], v[134:137], off offset:576 sc1
	s_nop 1
	v_lshlrev_b64 v[134:135], 12, v[226:227]
	v_lshl_add_u64 v[134:135], s[30:31], 0, v[134:135]
	v_lshl_add_u64 v[138:139], v[134:135], 0, v[196:197]
	v_pk_mul_f32 v[136:137], v[20:21], v[200:201]
	v_pk_mul_f32 v[134:135], v[18:19], v[198:199]
	global_store_dwordx4 v[138:139], v[134:137], off sc1
	s_nop 1
	v_pk_mul_f32 v[136:137], v[16:17], v[204:205]
	v_pk_mul_f32 v[134:135], v[14:15], v[202:203]
	global_store_dwordx4 v[138:139], v[134:137], off offset:64 sc1
	s_nop 1
	v_pk_mul_f32 v[136:137], v[12:13], v[212:213]
	v_pk_mul_f32 v[134:135], v[10:11], v[210:211]
	global_store_dwordx4 v[138:139], v[134:137], off offset:512 sc1
	s_nop 1
	v_pk_mul_f32 v[136:137], v[8:9], v[222:223]
	v_pk_mul_f32 v[134:135], v[6:7], v[220:221]
	global_store_dwordx4 v[138:139], v[134:137], off offset:576 sc1
	s_waitcnt vmcnt(0)
	s_barrier
	v_readfirstlane_b32 s30, v230
	s_lshr_b32 s30, s30, 6
	s_cmp_lg_u32 s30, 0
	s_cbranch_scc1 .Lsp_noinc
	v_readlane_b32 s30, v253, 41
	v_readlane_b32 s31, v253, 29
	s_lshl_b32 s30, s30, 1
	s_cmp_eq_u32 s31, 8
	s_cselect_b32 s31, 1, 0
	s_add_i32 s30, s30, s31
	s_lshl_b32 s30, s30, 2
	s_add_i32 s30, s30, s76
	s_add_i32 s30, s30, 0xffffffc0
	s_lshl_b32 s30, s30, 2
	s_add_i32 s34, s30, 0x8800
	v_readlane_b32 s30, v253, 42
	v_readlane_b32 s31, v253, 43
	s_add_u32 s30, s30, s34
	s_addc_u32 s31, s31, 0
	s_mov_b64 s[36:37], exec
	s_mov_b64 exec, 1
	v_mov_b32_e32 v134, 1
	s_nop 4
	global_atomic_add v1, v134, s[30:31]
	s_mov_b64 exec, s[36:37]

.LBB0_308:
	v_readlane_b32 s30, v253, 41
	v_readlane_b32 s31, v253, 29
	s_lshl_b32 s38, s30, 1
	s_cmp_eq_u32 s31, 8
	s_cselect_b32 s31, 1, 0
	s_add_i32 s38, s38, s31
	s_ashr_i32 s25, s76, 5
	s_mul_i32 s25, s25, 0x18000
	s_add_u32 s36, s18, s25
	s_addc_u32 s37, s19, 0
	v_lshlrev_b64 v[226:227], 2, v[194:195]
	v_ashrrev_i32_e32 v193, 31, v192
	v_lshlrev_b64 v[228:229], 12, v[192:193]
	v_lshl_add_u64 v[244:245], s[36:37], 0, v[226:227]
	global_load_dwordx4 v[198:201], v[244:245], off offset:0
	global_load_dwordx4 v[202:205], v[244:245], off offset:64
	global_load_dwordx4 v[210:213], v[244:245], off offset:512
	global_load_dwordx4 v[214:217], v[244:245], off offset:576
	v_lshl_add_u64 v[242:243], s[12:13], 0, v[226:227]
	v_lshl_add_u64 v[242:243], v[242:243], 0, v[228:229]
	s_mov_b32 s31, 0
	s_mov_b32 s30, 0x0
	v_lshl_add_u64 v[246:247], v[242:243], 0, s[30:31]
	global_load_dwordx4 v[134:137], v[246:247], off offset:0
	global_load_dwordx4 v[138:141], v[246:247], off offset:64
	global_load_dwordx4 v[142:145], v[246:247], off offset:512
	global_load_dwordx4 v[146:149], v[246:247], off offset:576
	s_mov_b32 s30, 0x10000
	v_lshl_add_u64 v[246:247], v[242:243], 0, s[30:31]
	global_load_dwordx4 v[150:153], v[246:247], off offset:0
	global_load_dwordx4 v[154:157], v[246:247], off offset:64
	global_load_dwordx4 v[158:161], v[246:247], off offset:512
	global_load_dwordx4 v[162:165], v[246:247], off offset:576
	s_mov_b32 s30, 0x20000
	v_lshl_add_u64 v[246:247], v[242:243], 0, s[30:31]
	global_load_dwordx4 v[166:169], v[246:247], off offset:0
	global_load_dwordx4 v[170:173], v[246:247], off offset:64
	global_load_dwordx4 v[174:177], v[246:247], off offset:512
	global_load_dwordx4 v[178:181], v[246:247], off offset:576
	s_mov_b32 s30, 0x30000
	v_lshl_add_u64 v[246:247], v[242:243], 0, s[30:31]
	global_load_dwordx4 v[182:185], v[246:247], off offset:0
	global_load_dwordx4 v[186:189], v[246:247], off offset:64
	global_load_dwordx4 v[190:193], v[246:247], off offset:512
	global_load_dwordx4 v[194:197], v[246:247], off offset:576
	ds_bpermute_b32 v6, v222, v6
	ds_bpermute_b32 v7, v222, v7
	ds_bpermute_b32 v8, v222, v8
	ds_bpermute_b32 v9, v222, v9
	ds_bpermute_b32 v10, v222, v10
	ds_bpermute_b32 v11, v222, v11
	ds_bpermute_b32 v12, v222, v12
	ds_bpermute_b32 v13, v222, v13
	ds_bpermute_b32 v14, v222, v14
	ds_bpermute_b32 v15, v222, v15
	ds_bpermute_b32 v16, v222, v16
	ds_bpermute_b32 v17, v222, v17
	ds_bpermute_b32 v18, v222, v18
	ds_bpermute_b32 v19, v222, v19
	ds_bpermute_b32 v20, v222, v20
	ds_bpermute_b32 v21, v222, v21
	s_waitcnt lgkmcnt(8)
	ds_bpermute_b32 v22, v222, v22
	ds_bpermute_b32 v23, v222, v23
	ds_bpermute_b32 v24, v222, v24
	ds_bpermute_b32 v25, v222, v25
	ds_bpermute_b32 v26, v222, v26
	ds_bpermute_b32 v27, v222, v27
	ds_bpermute_b32 v28, v222, v28
	ds_bpermute_b32 v29, v222, v29
	s_waitcnt lgkmcnt(8)
	ds_bpermute_b32 v30, v222, v30
	ds_bpermute_b32 v31, v222, v31
	ds_bpermute_b32 v32, v222, v32
	ds_bpermute_b32 v33, v222, v33
	ds_bpermute_b32 v34, v222, v34
	ds_bpermute_b32 v35, v222, v35
	ds_bpermute_b32 v36, v222, v36
	ds_bpermute_b32 v37, v222, v37
	s_waitcnt lgkmcnt(8)
	ds_bpermute_b32 v38, v222, v38
	ds_bpermute_b32 v39, v222, v39
	ds_bpermute_b32 v40, v222, v40
	ds_bpermute_b32 v41, v222, v41
	ds_bpermute_b32 v42, v222, v42
	ds_bpermute_b32 v43, v222, v43
	ds_bpermute_b32 v44, v222, v44
	ds_bpermute_b32 v45, v222, v45
	s_waitcnt lgkmcnt(8)
	ds_bpermute_b32 v46, v222, v46
	ds_bpermute_b32 v47, v222, v47
	ds_bpermute_b32 v48, v222, v48
	ds_bpermute_b32 v49, v222, v49
	ds_bpermute_b32 v50, v222, v50
	ds_bpermute_b32 v51, v222, v51
	ds_bpermute_b32 v52, v222, v52
	ds_bpermute_b32 v53, v222, v53
	s_waitcnt lgkmcnt(8)
	ds_bpermute_b32 v54, v222, v54
	ds_bpermute_b32 v55, v222, v55
	ds_bpermute_b32 v56, v222, v56
	ds_bpermute_b32 v57, v222, v57
	ds_bpermute_b32 v58, v222, v58
	ds_bpermute_b32 v59, v222, v59
	ds_bpermute_b32 v60, v222, v60
	ds_bpermute_b32 v61, v222, v61
	s_waitcnt lgkmcnt(8)
	ds_bpermute_b32 v62, v222, v62
	ds_bpermute_b32 v63, v222, v63
	ds_bpermute_b32 v64, v222, v64
	ds_bpermute_b32 v65, v222, v65
	ds_bpermute_b32 v66, v222, v66
	ds_bpermute_b32 v67, v222, v67
	ds_bpermute_b32 v68, v222, v68
	ds_bpermute_b32 v69, v222, v69
	s_waitcnt lgkmcnt(8)
	ds_bpermute_b32 v70, v222, v70
	ds_bpermute_b32 v71, v222, v71
	ds_bpermute_b32 v72, v222, v72
	ds_bpermute_b32 v73, v222, v73
	ds_bpermute_b32 v74, v222, v74
	ds_bpermute_b32 v75, v222, v75
	ds_bpermute_b32 v76, v222, v76
	ds_bpermute_b32 v77, v222, v77
	s_waitcnt lgkmcnt(8)
	ds_bpermute_b32 v78, v222, v78
	ds_bpermute_b32 v79, v222, v79
	ds_bpermute_b32 v80, v222, v80
	ds_bpermute_b32 v81, v222, v81
	ds_bpermute_b32 v82, v222, v82
	ds_bpermute_b32 v83, v222, v83
	ds_bpermute_b32 v84, v222, v84
	ds_bpermute_b32 v85, v222, v85
	s_waitcnt lgkmcnt(8)
	ds_bpermute_b32 v86, v222, v86
	ds_bpermute_b32 v87, v222, v87
	ds_bpermute_b32 v88, v222, v88
	ds_bpermute_b32 v89, v222, v89
	ds_bpermute_b32 v90, v222, v90
	ds_bpermute_b32 v91, v222, v91
	ds_bpermute_b32 v92, v222, v92
	ds_bpermute_b32 v93, v222, v93
	s_waitcnt lgkmcnt(8)
	ds_bpermute_b32 v94, v222, v94
	ds_bpermute_b32 v95, v222, v95
	ds_bpermute_b32 v96, v222, v96
	ds_bpermute_b32 v97, v222, v97
	ds_bpermute_b32 v98, v222, v98
	ds_bpermute_b32 v99, v222, v99
	ds_bpermute_b32 v100, v222, v100
	ds_bpermute_b32 v101, v222, v101
	s_waitcnt lgkmcnt(8)
	ds_bpermute_b32 v102, v222, v102
	ds_bpermute_b32 v103, v222, v103
	ds_bpermute_b32 v104, v222, v104
	ds_bpermute_b32 v105, v222, v105
	ds_bpermute_b32 v106, v222, v106
	ds_bpermute_b32 v107, v222, v107
	ds_bpermute_b32 v108, v222, v108
	ds_bpermute_b32 v109, v222, v109
	s_waitcnt lgkmcnt(8)
	ds_bpermute_b32 v110, v222, v110
	ds_bpermute_b32 v111, v222, v111
	ds_bpermute_b32 v112, v222, v112
	ds_bpermute_b32 v113, v222, v113
	ds_bpermute_b32 v114, v222, v114
	ds_bpermute_b32 v115, v222, v115
	ds_bpermute_b32 v116, v222, v116
	ds_bpermute_b32 v117, v222, v117
	s_waitcnt lgkmcnt(8)
	ds_bpermute_b32 v118, v222, v118
	ds_bpermute_b32 v119, v222, v119
	ds_bpermute_b32 v120, v222, v120
	ds_bpermute_b32 v121, v222, v121
	ds_bpermute_b32 v122, v222, v122
	ds_bpermute_b32 v123, v222, v123
	ds_bpermute_b32 v124, v222, v124
	ds_bpermute_b32 v125, v222, v125
	s_waitcnt lgkmcnt(8)
	ds_bpermute_b32 v126, v222, v126
	ds_bpermute_b32 v127, v222, v127
	ds_bpermute_b32 v128, v222, v128
	ds_bpermute_b32 v129, v222, v129
	ds_bpermute_b32 v130, v222, v130
	ds_bpermute_b32 v131, v222, v131
	ds_bpermute_b32 v132, v222, v132
	ds_bpermute_b32 v133, v222, v133
	s_waitcnt lgkmcnt(0)
	s_waitcnt vmcnt(0)
	v_pk_fma_f32 v[130:131], v[130:131], v[198:199], v[134:135]
	v_pk_fma_f32 v[132:133], v[132:133], v[200:201], v[136:137]
	v_pk_fma_f32 v[126:127], v[126:127], v[202:203], v[138:139]
	v_pk_fma_f32 v[128:129], v[128:129], v[204:205], v[140:141]
	v_pk_fma_f32 v[122:123], v[122:123], v[210:211], v[142:143]
	v_pk_fma_f32 v[124:125], v[124:125], v[212:213], v[144:145]
	v_pk_fma_f32 v[118:119], v[118:119], v[214:215], v[146:147]
	v_pk_fma_f32 v[120:121], v[120:121], v[216:217], v[148:149]
	v_pk_fma_f32 v[114:115], v[114:115], v[198:199], v[150:151]
	v_pk_fma_f32 v[116:117], v[116:117], v[200:201], v[152:153]
	v_pk_fma_f32 v[110:111], v[110:111], v[202:203], v[154:155]
	v_pk_fma_f32 v[112:113], v[112:113], v[204:205], v[156:157]
	v_pk_fma_f32 v[106:107], v[106:107], v[210:211], v[158:159]
	v_pk_fma_f32 v[108:109], v[108:109], v[212:213], v[160:161]
	v_pk_fma_f32 v[102:103], v[102:103], v[214:215], v[162:163]
	v_pk_fma_f32 v[104:105], v[104:105], v[216:217], v[164:165]
	v_pk_fma_f32 v[98:99], v[98:99], v[198:199], v[166:167]
	v_pk_fma_f32 v[100:101], v[100:101], v[200:201], v[168:169]
	v_pk_fma_f32 v[94:95], v[94:95], v[202:203], v[170:171]
	v_pk_fma_f32 v[96:97], v[96:97], v[204:205], v[172:173]
	v_pk_fma_f32 v[90:91], v[90:91], v[210:211], v[174:175]
	v_pk_fma_f32 v[92:93], v[92:93], v[212:213], v[176:177]
	v_pk_fma_f32 v[86:87], v[86:87], v[214:215], v[178:179]
	v_pk_fma_f32 v[88:89], v[88:89], v[216:217], v[180:181]
	v_pk_fma_f32 v[82:83], v[82:83], v[198:199], v[182:183]
	v_pk_fma_f32 v[84:85], v[84:85], v[200:201], v[184:185]
	v_pk_fma_f32 v[78:79], v[78:79], v[202:203], v[186:187]
	v_pk_fma_f32 v[80:81], v[80:81], v[204:205], v[188:189]
	v_pk_fma_f32 v[74:75], v[74:75], v[210:211], v[190:191]
	v_pk_fma_f32 v[76:77], v[76:77], v[212:213], v[192:193]
	v_pk_fma_f32 v[70:71], v[70:71], v[214:215], v[194:195]
	v_pk_fma_f32 v[72:73], v[72:73], v[216:217], v[196:197]
	s_mov_b32 s30, 0x80000
	v_lshl_add_u64 v[246:247], v[242:243], 0, s[30:31]
	global_load_dwordx4 v[134:137], v[246:247], off offset:0
	global_load_dwordx4 v[138:141], v[246:247], off offset:64
	global_load_dwordx4 v[142:145], v[246:247], off offset:512
	global_load_dwordx4 v[146:149], v[246:247], off offset:576
	s_mov_b32 s30, 0x90000
	v_lshl_add_u64 v[246:247], v[242:243], 0, s[30:31]
	global_load_dwordx4 v[150:153], v[246:247], off offset:0
	global_load_dwordx4 v[154:157], v[246:247], off offset:64
	global_load_dwordx4 v[158:161], v[246:247], off offset:512
	global_load_dwordx4 v[162:165], v[246:247], off offset:576
	s_mov_b32 s30, 0xa0000
	v_lshl_add_u64 v[246:247], v[242:243], 0, s[30:31]
	global_load_dwordx4 v[166:169], v[246:247], off offset:0
	global_load_dwordx4 v[170:173], v[246:247], off offset:64
	global_load_dwordx4 v[174:177], v[246:247], off offset:512
	global_load_dwordx4 v[178:181], v[246:247], off offset:576
	s_mov_b32 s30, 0xb0000
	v_lshl_add_u64 v[246:247], v[242:243], 0, s[30:31]
	global_load_dwordx4 v[182:185], v[246:247], off offset:0
	global_load_dwordx4 v[186:189], v[246:247], off offset:64
	global_load_dwordx4 v[190:193], v[246:247], off offset:512
	global_load_dwordx4 v[194:197], v[246:247], off offset:576
	s_waitcnt vmcnt(0)
	v_pk_fma_f32 v[66:67], v[66:67], v[198:199], v[134:135]
	v_pk_fma_f32 v[68:69], v[68:69], v[200:201], v[136:137]
	v_pk_fma_f32 v[62:63], v[62:63], v[202:203], v[138:139]
	v_pk_fma_f32 v[64:65], v[64:65], v[204:205], v[140:141]
	v_pk_fma_f32 v[58:59], v[58:59], v[210:211], v[142:143]
	v_pk_fma_f32 v[60:61], v[60:61], v[212:213], v[144:145]
	v_pk_fma_f32 v[54:55], v[54:55], v[214:215], v[146:147]
	v_pk_fma_f32 v[56:57], v[56:57], v[216:217], v[148:149]
	v_pk_fma_f32 v[50:51], v[50:51], v[198:199], v[150:151]
	v_pk_fma_f32 v[52:53], v[52:53], v[200:201], v[152:153]
	v_pk_fma_f32 v[46:47], v[46:47], v[202:203], v[154:155]
	v_pk_fma_f32 v[48:49], v[48:49], v[204:205], v[156:157]
	v_pk_fma_f32 v[42:43], v[42:43], v[210:211], v[158:159]
	v_pk_fma_f32 v[44:45], v[44:45], v[212:213], v[160:161]
	v_pk_fma_f32 v[38:39], v[38:39], v[214:215], v[162:163]
	v_pk_fma_f32 v[40:41], v[40:41], v[216:217], v[164:165]
	v_pk_fma_f32 v[34:35], v[34:35], v[198:199], v[166:167]
	v_pk_fma_f32 v[36:37], v[36:37], v[200:201], v[168:169]
	v_pk_fma_f32 v[30:31], v[30:31], v[202:203], v[170:171]
	v_pk_fma_f32 v[32:33], v[32:33], v[204:205], v[172:173]
	v_pk_fma_f32 v[26:27], v[26:27], v[210:211], v[174:175]
	v_pk_fma_f32 v[28:29], v[28:29], v[212:213], v[176:177]
	v_pk_fma_f32 v[22:23], v[22:23], v[214:215], v[178:179]
	v_pk_fma_f32 v[24:25], v[24:25], v[216:217], v[180:181]
	v_pk_fma_f32 v[18:19], v[18:19], v[198:199], v[182:183]
	v_pk_fma_f32 v[20:21], v[20:21], v[200:201], v[184:185]
	v_pk_fma_f32 v[14:15], v[14:15], v[202:203], v[186:187]
	v_pk_fma_f32 v[16:17], v[16:17], v[204:205], v[188:189]
	v_pk_fma_f32 v[10:11], v[10:11], v[210:211], v[190:191]
	v_pk_fma_f32 v[12:13], v[12:13], v[212:213], v[192:193]
	v_pk_fma_f32 v[6:7], v[6:7], v[214:215], v[194:195]
	v_pk_fma_f32 v[8:9], v[8:9], v[216:217], v[196:197]
	s_cmp_eq_u32 s38, 7
	s_cbranch_scc1 .Lrn_final_p
	s_and_b32 s25, s38, 1
	s_lshr_b32 s30, s38, 1
	s_cmp_eq_u32 s25, 0
	s_cbranch_scc1 .Lrn_ffn_p
	s_add_i32 s30, s30, 1
	s_movk_i32 s25, 0x48
	s_mul_i32 s31, s30, 0x6000
	s_branch .Lrn_p_done
